# v46 + P0 roles assigned by an XCD-interleaved index (each XCD: 18 adaLN + 14 weight-copy workgroups instead of whole XCDs per role)
# baseline (speedup 1.0000x reference)
.LBB0_8:
	s_cmpk_eq_i32 s78, 0x100
	s_load_dwordx16 s[80:95], s[0:1], 0x0
	s_cselect_b64 s[0:1], -1, 0
	v_writelane_b32 v246, s0, 17
	s_cmpk_lg_i32 s78, 0x100
	v_lshrrev_b32_e32 v209, 6, v236
	v_writelane_b32 v246, s1, 18
	s_cselect_b64 s[0:1], -1, 0
	v_writelane_b32 v246, s0, 19
	s_cmp_lt_i32 s76, 1
	v_and_b32_e32 v208, 63, v236
	v_writelane_b32 v246, s1, 20
	s_waitcnt lgkmcnt(0)
	v_writelane_b32 v246, s80, 21
	s_cselect_b64 s[0:1], -1, 0
	s_cmp_gt_i32 s77, 0
	v_writelane_b32 v246, s81, 22
	v_writelane_b32 v246, s82, 23
	v_writelane_b32 v246, s83, 24
	v_writelane_b32 v246, s84, 25
	v_writelane_b32 v246, s85, 26
	v_writelane_b32 v246, s86, 27
	v_writelane_b32 v246, s87, 28
	v_writelane_b32 v246, s88, 29
	v_writelane_b32 v246, s89, 30
	v_writelane_b32 v246, s90, 31
	v_writelane_b32 v246, s91, 32
	s_cselect_b64 s[2:3], -1, 0
	v_writelane_b32 v246, s92, 33
	s_and_b64 s[0:1], s[0:1], s[2:3]
	v_writelane_b32 v246, s93, 34
	s_andn2_b64 vcc, exec, s[0:1]
	v_writelane_b32 v246, s94, 35
	v_writelane_b32 v246, s95, 36
	s_mov_b32 s101, s97
	s_cbranch_vccnz .LBB0_149
	s_cmpk_lg_i32 s78, 0x100
	s_cbranch_scc1 .Lp0x_keep
	s_and_b32 s97, s101, 31
	s_lshl_b32 s97, s97, 3
	s_lshr_b32 s100, s101, 5
	s_add_i32 s97, s97, s100
.Lp0x_keep:
	s_cmpk_gt_i32 s97, 0x8f
	s_cselect_b64 s[36:37], -1, 0
	s_and_b64 vcc, exec, s[36:37]
	s_cbranch_vccnz .LBB0_35
	v_and_b32_e32 v1, 31, v236
	v_bfe_u32 v6, v236, 5, 1
	v_lshlrev_b32_e32 v2, 2, v1
	v_lshl_or_b32 v1, v209, 7, v6
	v_mul_u32_u24_e32 v3, 0x2400, v1
	v_readlane_b32 s8, v246, 1
	v_lshlrev_b32_e32 v98, 2, v3
	v_mov_b32_e32 v99, 0
	v_readlane_b32 s9, v246, 2
	v_mov_b32_e32 v3, v99
	v_add_u32_e32 v7, 0x200, v236
	v_lshl_add_u64 v[4:5], s[8:9], 0, v[98:99]
	v_lshl_add_u64 v[100:101], v[4:5], 0, v[2:3]
	v_lshl_add_u32 v3, v209, 13, 0
	v_lshlrev_b32_e32 v4, 10, v6
	v_add3_u32 v108, v3, v4, v2
	v_and_b32_e32 v3, 7, v236
	v_lshrrev_b32_e32 v7, 3, v7
	v_lshrrev_b32_e32 v8, 3, v236
	v_mul_u32_u24_e32 v8, 0x84, v8
	v_mul_u32_u24_e32 v7, 0x84, v7
	v_lshlrev_b32_e32 v3, 2, v3
	v_add3_u32 v109, 0, v8, v3
	v_add3_u32 v110, 0, v7, v3
	v_or_b32_e32 v7, 0x400, v236
	v_add_u32_e32 v8, 0x600, v236
	v_lshrrev_b32_e32 v8, 3, v8
	v_lshrrev_b32_e32 v7, 3, v7
	v_mul_u32_u24_e32 v7, 0x84, v7
	v_mul_u32_u24_e32 v8, 0x84, v8
	v_add3_u32 v111, 0, v7, v3
	v_add3_u32 v112, 0, v8, v3
	v_or_b32_e32 v7, 0x800, v236
	v_add_u32_e32 v8, 0xa00, v236
	v_lshrrev_b32_e32 v8, 3, v8
	v_lshrrev_b32_e32 v7, 3, v7
	v_mul_u32_u24_e32 v7, 0x84, v7
	v_mul_u32_u24_e32 v8, 0x84, v8
	v_add3_u32 v113, 0, v7, v3
	v_add3_u32 v114, 0, v8, v3
	v_or_b32_e32 v7, 0xc00, v236
	v_add_u32_e32 v8, 0xe00, v236
	v_lshrrev_b32_e32 v8, 3, v8
	v_lshrrev_b32_e32 v7, 3, v7
	v_mul_u32_u24_e32 v7, 0x84, v7
	v_mul_u32_u24_e32 v8, 0x84, v8
	v_add3_u32 v115, 0, v7, v3
	v_add3_u32 v116, 0, v8, v3
	v_or_b32_e32 v7, 0x1000, v236
	v_add_u32_e32 v8, 0x1200, v236
	v_lshrrev_b32_e32 v8, 3, v8
	v_lshrrev_b32_e32 v7, 3, v7
	v_mul_u32_u24_e32 v7, 0x84, v7
	v_mul_u32_u24_e32 v8, 0x84, v8
	v_add3_u32 v117, 0, v7, v3
	v_add3_u32 v118, 0, v8, v3
	v_or_b32_e32 v7, 0x1400, v236
	v_add_u32_e32 v8, 0x1600, v236
	v_lshrrev_b32_e32 v8, 3, v8
	v_lshrrev_b32_e32 v7, 3, v7
	v_xor_b32_e32 v5, 0x5fff, v236
	v_mul_u32_u24_e32 v7, 0x84, v7
	v_mul_u32_u24_e32 v8, 0x84, v8
	v_lshrrev_b32_e32 v4, 9, v236
	v_lshrrev_b32_e32 v5, 9, v5
	s_movk_i32 s0, 0xe00
	v_mov_b32_e32 v6, 0x5fff
	v_add3_u32 v119, 0, v7, v3
	v_add3_u32 v120, 0, v8, v3
	v_or_b32_e32 v7, 0x1800, v236
	v_add_u32_e32 v8, 0x1a00, v236
	v_sub_u32_e32 v4, 16, v4
	v_add_u32_e32 v5, 1, v5
	v_bitop3_b32 v6, v236, s0, v6 bitop3:0x48
	v_lshrrev_b32_e32 v8, 3, v8
	v_lshrrev_b32_e32 v7, 3, v7
	v_and_b32_e32 v5, 7, v5
	v_cmp_ne_u32_e64 s[0:1], s0, v6
	v_and_b32_e32 v6, 30, v4
	v_mul_u32_u24_e32 v7, 0x84, v7
	v_mul_u32_u24_e32 v8, 0x84, v8
	v_add3_u32 v121, 0, v7, v3
	v_add3_u32 v122, 0, v8, v3
	v_or_b32_e32 v7, 0x1c00, v236
	v_add_u32_e32 v8, 0x1e00, v236
	v_sub_u32_e32 v125, 0, v5
	v_lshl_or_b32 v5, v6, 9, v236
	v_lshrrev_b32_e32 v8, 3, v8
	v_lshrrev_b32_e32 v7, 3, v7
	v_add_u32_e32 v126, 0xfffffe00, v5
	v_lshrrev_b32_e32 v5, 3, v5
	v_mul_u32_u24_e32 v1, 0x84, v1
	v_mul_u32_u24_e32 v7, 0x84, v7
	v_mul_u32_u24_e32 v8, 0x84, v8
	v_mul_u32_u24_e32 v5, 0x84, v5
	v_add3_u32 v1, 0, v2, v1
	v_add3_u32 v123, 0, v7, v3
	v_add3_u32 v124, 0, v8, v3
	v_add3_u32 v3, v5, v3, 0
	v_or_b32_e32 v98, v98, v2
	v_mul_u32_u24_e32 v2, 0x9000, v209
	v_lshlrev_b32_e32 v5, 2, v208
	v_add_u32_e32 v127, 0x60, v3
	v_mul_hi_u32_u24_e32 v3, 0x9000, v209
	v_or_b32_e32 v2, v2, v5
	v_readlane_b32 s10, v246, 3
	v_readlane_b32 s11, v246, 4
	v_readlane_b32 s12, v246, 5
	v_readlane_b32 s13, v246, 6
	v_readlane_b32 s14, v246, 7
	v_readlane_b32 s15, v246, 8
	v_readlane_b32 s16, v246, 9
	v_readlane_b32 s17, v246, 10
	v_lshl_add_u64 v[104:105], s[74:75], 0, v[2:3]
	v_lshl_or_b32 v2, v209, 8, v5
	s_movk_i32 s33, 0x84
	v_cmp_ne_u32_e64 s[2:3], 2, v6
	v_cmp_ne_u32_e64 s[4:5], 4, v6
	v_cmp_ne_u32_e64 s[6:7], 6, v6
	v_lshl_add_u64 v[102:103], s[8:9], 0, v[98:99]
	s_lshl_b32 s42, s78, 6
	v_add_u32_e32 v128, 0xfffffe00, v236
	v_add_u32_e32 v129, 0, v2
	s_movk_i32 s43, 0x2000
	v_mov_b32_e32 v130, 0x3ff
	s_movk_i32 s44, 0x7c00
	v_mov_b32_e32 v131, s95
	v_mov_b32_e32 v132, s93
	s_mov_b32 s45, s97
	v_cmp_ne_u32_e64 s[8:9], 8, v6
	v_cmp_ne_u32_e64 s[10:11], 10, v6
	v_cmp_ne_u32_e64 s[12:13], 12, v6
	v_cmp_ne_u32_e64 s[14:15], 14, v6
	v_cmp_ne_u32_e64 s[16:17], v4, v6
	s_lshl_b32 s38, s97, 6
	v_readlane_b32 s18, v246, 11
	v_readlane_b32 s19, v246, 12
	v_readlane_b32 s20, v246, 13
	v_readlane_b32 s21, v246, 14
	v_readlane_b32 s22, v246, 15
	v_readlane_b32 s23, v246, 16

.LBB0_149:
	s_mov_b32 s97, s101
	v_cmp_gt_u32_e32 vcc, 2, v236
	s_and_saveexec_b64 s[0:1], vcc
	v_lshl_add_u32 v1, v236, 2, 0
	v_add_u32_e32 v1, 0x23f40, v1
	v_mov_b32_e32 v2, 0
	ds_write_b32 v1, v2
	s_or_b64 exec, exec, s[0:1]
	v_lshrrev_b32_e32 v1, 20, v0
	v_lshrrev_b32_e32 v0, 10, v0
	v_or_b32_e32 v0, v0, v1
	s_movk_i32 s0, 0x3ff
	v_and_or_b32 v0, v0, s0, v236
	v_cmp_eq_u32_e32 vcc, 0, v0
	s_waitcnt lgkmcnt(0)
	s_barrier
	s_and_saveexec_b64 s[0:1], vcc
	s_cbranch_execz .LBB0_161
	buffer_wbl2 sc1
	s_waitcnt vmcnt(0)
	s_load_dwordx2 s[2:3], s[34:35], 0x58
	v_mov_b32_e32 v2, 0
	s_mov_b64 s[4:5], exec
	v_mbcnt_lo_u32_b32 v1, s4, 0
	v_mbcnt_hi_u32_b32 v1, s5, v1
	s_waitcnt lgkmcnt(0)
	global_load_dword v0, v2, s[2:3] offset:40
	v_cmp_eq_u32_e32 vcc, 0, v1
	s_and_saveexec_b64 s[6:7], vcc
	s_cbranch_execz .LBB0_154
	s_bcnt1_i32_b64 s4, s[4:5]
	v_mov_b32_e32 v3, s4
	global_atomic_add v3, v2, v3, s[2:3] offset:32 sc0
